# P4: second A half of the next unit's K-step-1 tile staged at the end of the previous K loop; the first K-step's counted vmcnt wait (which also waited for the previous epilogue's store drain) dropped
# baseline (speedup 1.0000x reference)
.LBB0_455:
	s_add_u32 s26, s26, 0x13000000
	s_addc_u32 s27, s27, 0
	s_add_u32 s28, s28, 0x3000000
	s_addc_u32 s29, s29, 0
	s_add_u32 s30, s30, 0x100000
	s_addc_u32 s31, s31, 0
	s_waitcnt lgkmcnt(0)
	s_add_u32 s34, s34, 0xd4000
	s_addc_u32 s35, s35, 0
	s_add_u32 s36, s36, 0x20000
	s_addc_u32 s37, s37, 0
	s_add_u32 s38, s38, 0x7000000
	s_addc_u32 s39, s39, 0
	s_add_u32 s40, s40, 0xf000000
	s_addc_u32 s41, s41, 0
	s_lshr_b32 s5, s5, 26
	s_mov_b64 s[42:43], 0x80
	s_and_b32 s17, s17, 3
	s_add_i32 s5, s4, s5
	s_add_i32 m0, s93, 0x18000
	v_lshl_add_u64 v[6:7], v[6:7], 0, s[42:43]
	s_ashr_i32 s95, s5, 6
	s_lshl_b32 s5, s20, 13
	s_lshl_b32 s96, s17, 5
	s_lshl_b32 s19, s17, 12
	s_waitcnt vmcnt(4)
	s_barrier
	global_load_lds_dwordx4 v[6:7], off
	v_lshl_add_u64 v[4:5], v[4:5], 0, s[42:43]
	s_add_i32 m0, s93, 0x1a000
	s_add_i32 s97, s93, 0x8000
	s_add_i32 s18, s93, 0xa000
	global_load_lds_dwordx4 v[4:5], off
	v_lshl_add_u64 v[0:1], v[0:1], 0, s[42:43]
	s_mov_b32 m0, s97
	s_add_u32 s44, s8, 0x10080
	global_load_lds_dwordx4 v[0:1], off
	v_lshl_add_u64 v[0:1], v[2:3], 0, s[42:43]
	s_mov_b32 m0, s18
	s_addc_u32 s45, s9, 0
	global_load_lds_dwordx4 v[0:1], off
	s_add_i32 m0, s93, 0x1c000
	v_lshl_add_u64 v[0:1], s[44:45], 0, v[158:159]
	global_load_lds_dwordx4 v[0:1], off
	v_lshl_add_u64 v[0:1], s[44:45], 0, v[162:163]
	s_add_i32 m0, s93, 0x1e000
	v_and_b32_e32 v224, 15, v8
	global_load_lds_dwordx4 v[0:1], off
	v_bfe_u32 v225, v8, 4, 2
	v_lshlrev_b32_e32 v0, 6, v224
	v_lshlrev_b32_e32 v1, 2, v8
	v_lshl_or_b32 v0, v225, 4, v0
	v_and_b32_e32 v1, 32, v1
	s_cmp_gt_i32 s4, 63
	v_bitop3_b32 v228, v0, s19, v1 bitop3:0xde
	s_cselect_b64 s[44:45], -1, 0
	s_add_i32 s19, s95, -2
	s_cmpk_lt_u32 s16, 0x100
	v_bitop3_b32 v2, v0, s5, v1 bitop3:0xde
	s_cselect_b64 s[46:47], -1, 0
	s_lshl_b32 s16, s20, 7
	v_lshlrev_b32_e32 v0, 12, v10
	v_lshlrev_b32_e32 v1, 14, v12
	s_mov_b32 s20, 0xfffc0000
	v_and_or_b32 v0, v0, s20, v1
	v_add3_u32 v1, v13, v9, v11
	s_lshl_b32 s4, s17, 8
	v_lshl_add_u32 v164, v1, 1, v0
	v_lshlrev_b32_e32 v0, 12, v14
	v_lshlrev_b32_e32 v1, 14, v15
	s_waitcnt vmcnt(6)
	s_add_i32 s17, s4, 0
	s_mov_b64 s[4:5], 0x2080
	v_and_or_b32 v0, v0, s20, v1
	v_lshl_add_u64 v[166:167], v[164:165], 0, s[4:5]
	v_add_u32_e32 v164, v0, v16
	s_add_i32 s88, 0, 0x10000
	s_add_i32 s89, 0, 0x14000
	s_add_i32 s17, s17, 0x20010
	v_lshl_add_u64 v[168:169], v[164:165], 0, s[4:5]
	v_add_u32_e32 v229, s88, v228
	v_add_u32_e32 v230, 0, v2
	v_add_u32_e32 v231, s89, v228
	s_mov_b32 s48, 0xbfb8aa3b
	s_mov_b32 s50, 0x3fb8aa3b
	v_mbcnt_hi_u32_b32 v227, -1, v222
	s_mov_b32 s62, s49
	s_mov_b32 s63, s10
	s_mov_b64 s[56:57], s[6:7]
	v_lshl_add_u64 v[190:191], s[6:7], 0, v[166:167]
	s_add_i32 m0, s93, 0xc000
	s_nop 0
	global_load_lds_dwordx4 v[190:191], off
	v_lshl_add_u64 v[192:193], s[6:7], 0, v[168:169]
	s_add_i32 m0, s93, 0xe000
	s_nop 0
	global_load_lds_dwordx4 v[192:193], off
	s_waitcnt vmcnt(0)
	s_barrier
	s_branch .LBB0_457

.Lpz_P4:
	s_and_b64 s[4:5], s[4:5], exec
	s_cselect_b32 s53, s59, s9
	s_cselect_b32 s55, s58, s8
	s_add_u32 s64, s8, 0x100
	s_addc_u32 s65, s9, 0
	s_mov_b32 s8, 0
	ds_read_b128 v[92:95], v229
	ds_read_b128 v[112:115], v229 offset:1024
	ds_read_b128 v[132:135], v229 offset:2048
	ds_read_b128 v[140:143], v229 offset:3072
	s_add_i32 s66, s8, 2
	s_add_u32 s4, s6, 0x100
	s_addc_u32 s5, s7, 0
	s_cmp_eq_u32 s19, s8
	s_cselect_b32 s8, s55, s64
	s_cselect_b32 s61, s57, s5
	s_cselect_b32 s60, s56, s4
	s_cselect_b32 s9, s53, s65
	ds_read_b128 v[144:147], v230
	ds_read_b128 v[148:151], v230 offset:1024
	ds_read_b128 v[152:155], v230 offset:2048
	ds_read_b128 v[170:173], v230 offset:3072
	ds_read_b128 v[174:177], v230 offset:4096
	ds_read_b128 v[178:181], v230 offset:5120
	ds_read_b128 v[182:185], v230 offset:6144
	ds_read_b128 v[186:189], v230 offset:7168
	s_waitcnt lgkmcnt(8)
	s_setprio 1
	s_barrier
	s_waitcnt lgkmcnt(0)
	v_mfma_f32_16x16x32_bf16 v[136:139], v[92:95], v[144:147], 0
	v_mfma_f32_16x16x32_bf16 v[124:127], v[132:135], v[144:147], 0
	v_mfma_f32_16x16x32_bf16 v[116:119], v[92:95], v[152:155], 0
	v_mfma_f32_16x16x32_bf16 v[104:107], v[132:135], v[152:155], 0
	v_mfma_f32_16x16x32_bf16 v[96:99], v[92:95], v[174:177], 0
	v_mfma_f32_16x16x32_bf16 v[84:87], v[132:135], v[174:177], 0
	v_mfma_f32_16x16x32_bf16 v[76:79], v[92:95], v[182:185], 0
	v_mfma_f32_16x16x32_bf16 v[68:71], v[132:135], v[182:185], 0
	v_mfma_f32_16x16x32_bf16 v[136:139], v[112:115], v[148:151], v[136:139]
	v_mfma_f32_16x16x32_bf16 v[124:127], v[140:143], v[148:151], v[124:127]
	v_mfma_f32_16x16x32_bf16 v[116:119], v[112:115], v[170:173], v[116:119]
	v_mfma_f32_16x16x32_bf16 v[104:107], v[140:143], v[170:173], v[104:107]
	v_mfma_f32_16x16x32_bf16 v[96:99], v[112:115], v[178:181], v[96:99]
	v_mfma_f32_16x16x32_bf16 v[84:87], v[140:143], v[178:181], v[84:87]
	v_mfma_f32_16x16x32_bf16 v[76:79], v[112:115], v[186:189], v[76:79]
	v_mfma_f32_16x16x32_bf16 v[68:71], v[140:143], v[186:189], v[68:71]
	s_barrier
	s_setprio 0
	s_add_i32 s6, s88, s92
	v_lshl_add_u64 v[206:207], s[8:9], 0, v[158:159]
	s_mov_b32 m0, s6
	ds_read_b128 v[190:193], v231
	ds_read_b128 v[194:197], v231 offset:1024
	ds_read_b128 v[198:201], v231 offset:2048
	ds_read_b128 v[202:205], v231 offset:3072
	global_load_lds_dwordx4 v[206:207], off
	v_lshl_add_u64 v[208:209], s[8:9], 0, v[162:163]
	s_add_i32 m0, s6, 0x2000
	s_nop 0
	global_load_lds_dwordx4 v[208:209], off
	s_waitcnt lgkmcnt(0)
	s_setprio 1
	s_barrier
	v_mfma_f32_16x16x32_bf16 v[128:131], v[190:193], v[144:147], 0
	v_mfma_f32_16x16x32_bf16 v[120:123], v[198:201], v[144:147], 0
	v_mfma_f32_16x16x32_bf16 v[108:111], v[190:193], v[152:155], 0
	v_mfma_f32_16x16x32_bf16 v[100:103], v[198:201], v[152:155], 0
	v_mfma_f32_16x16x32_bf16 v[88:91], v[190:193], v[174:177], 0
	v_mfma_f32_16x16x32_bf16 v[80:83], v[198:201], v[174:177], 0
	v_mfma_f32_16x16x32_bf16 v[72:75], v[190:193], v[182:185], 0
	v_mfma_f32_16x16x32_bf16 v[64:67], v[198:201], v[182:185], 0
	v_mfma_f32_16x16x32_bf16 v[128:131], v[194:197], v[148:151], v[128:131]
	v_mfma_f32_16x16x32_bf16 v[120:123], v[202:205], v[148:151], v[120:123]
	v_mfma_f32_16x16x32_bf16 v[108:111], v[194:197], v[170:173], v[108:111]
	v_mfma_f32_16x16x32_bf16 v[100:103], v[202:205], v[170:173], v[100:103]
	v_mfma_f32_16x16x32_bf16 v[88:91], v[194:197], v[178:181], v[88:91]
	v_mfma_f32_16x16x32_bf16 v[80:83], v[202:205], v[178:181], v[80:83]
	v_mfma_f32_16x16x32_bf16 v[72:75], v[194:197], v[186:189], v[72:75]
	v_mfma_f32_16x16x32_bf16 v[64:67], v[202:205], v[186:189], v[64:67]
	s_mov_b32 m0, s93
	v_lshl_add_u64 v[210:211], s[60:61], 0, v[156:157]
	s_barrier
	s_setprio 0
	ds_read_b128 v[144:147], v230 offset:16384
	ds_read_b128 v[148:151], v230 offset:17408
	ds_read_b128 v[152:155], v230 offset:18432
	ds_read_b128 v[170:173], v230 offset:19456
	ds_read_b128 v[174:177], v230 offset:20480
	ds_read_b128 v[178:181], v230 offset:21504
	ds_read_b128 v[182:185], v230 offset:22528
	ds_read_b128 v[186:189], v230 offset:23552
	global_load_lds_dwordx4 v[210:211], off
	v_lshl_add_u64 v[212:213], s[60:61], 0, v[160:161]
	s_mov_b32 m0, s84
	s_nop 0
	global_load_lds_dwordx4 v[212:213], off
	s_waitcnt lgkmcnt(0)
	s_setprio 1
	s_barrier
	v_mfma_f32_16x16x32_bf16 v[60:63], v[92:95], v[144:147], 0
	v_mfma_f32_16x16x32_bf16 v[52:55], v[132:135], v[144:147], 0
	v_mfma_f32_16x16x32_bf16 v[44:47], v[92:95], v[152:155], 0
	v_mfma_f32_16x16x32_bf16 v[36:39], v[132:135], v[152:155], 0
	v_mfma_f32_16x16x32_bf16 v[28:31], v[92:95], v[174:177], 0
	v_mfma_f32_16x16x32_bf16 v[20:23], v[132:135], v[174:177], 0
	v_mfma_f32_16x16x32_bf16 v[12:15], v[92:95], v[182:185], 0
	v_mfma_f32_16x16x32_bf16 v[4:7], v[132:135], v[182:185], 0
	v_mfma_f32_16x16x32_bf16 v[60:63], v[112:115], v[148:151], v[60:63]
	v_mfma_f32_16x16x32_bf16 v[52:55], v[140:143], v[148:151], v[52:55]
	v_mfma_f32_16x16x32_bf16 v[44:47], v[112:115], v[170:173], v[44:47]
	v_mfma_f32_16x16x32_bf16 v[36:39], v[140:143], v[170:173], v[36:39]
	v_mfma_f32_16x16x32_bf16 v[28:31], v[112:115], v[178:181], v[28:31]
	v_mfma_f32_16x16x32_bf16 v[20:23], v[140:143], v[178:181], v[20:23]
	v_mfma_f32_16x16x32_bf16 v[12:15], v[112:115], v[186:189], v[12:15]
	v_mfma_f32_16x16x32_bf16 v[4:7], v[140:143], v[186:189], v[4:7]
	s_barrier
	s_setprio 0
	s_add_u32 s6, s8, 0x10000
	s_addc_u32 s7, s9, 0
	s_add_i32 s20, s89, s92
	v_lshl_add_u64 v[92:93], s[6:7], 0, v[158:159]
	s_mov_b32 m0, s20
	s_nop 0
	global_load_lds_dwordx4 v[92:93], off
	v_lshl_add_u64 v[92:93], s[6:7], 0, v[162:163]
	s_add_i32 m0, s20, 0x2000
	s_nop 0
	global_load_lds_dwordx4 v[92:93], off
	s_setprio 1
	s_barrier
	v_mfma_f32_16x16x32_bf16 v[56:59], v[190:193], v[144:147], 0
	v_mfma_f32_16x16x32_bf16 v[48:51], v[198:201], v[144:147], 0
	v_mfma_f32_16x16x32_bf16 v[40:43], v[190:193], v[152:155], 0
	v_mfma_f32_16x16x32_bf16 v[32:35], v[198:201], v[152:155], 0
	v_mfma_f32_16x16x32_bf16 v[24:27], v[190:193], v[174:177], 0
	v_mfma_f32_16x16x32_bf16 v[16:19], v[198:201], v[174:177], 0
	v_mfma_f32_16x16x32_bf16 v[8:11], v[190:193], v[182:185], 0
	v_mfma_f32_16x16x32_bf16 v[0:3], v[198:201], v[182:185], 0
	v_mfma_f32_16x16x32_bf16 v[56:59], v[194:197], v[148:151], v[56:59]
	v_mfma_f32_16x16x32_bf16 v[48:51], v[202:205], v[148:151], v[48:51]
	v_mfma_f32_16x16x32_bf16 v[40:43], v[194:197], v[170:173], v[40:43]
	v_mfma_f32_16x16x32_bf16 v[32:35], v[202:205], v[170:173], v[32:35]
	v_mfma_f32_16x16x32_bf16 v[24:27], v[194:197], v[178:181], v[24:27]
	v_mfma_f32_16x16x32_bf16 v[16:19], v[202:205], v[178:181], v[16:19]
	v_mfma_f32_16x16x32_bf16 v[8:11], v[194:197], v[186:189], v[8:11]
	v_mfma_f32_16x16x32_bf16 v[0:3], v[202:205], v[186:189], v[0:3]
	s_add_i32 s20, 0, 0x18000
	v_add_u32_e32 v140, s20, v228
	s_barrier
	s_setprio 0
	ds_read_b128 v[92:95], v140
	ds_read_b128 v[112:115], v140 offset:1024
	ds_read_b128 v[132:135], v140 offset:2048
	ds_read_b128 v[140:143], v140 offset:3072
	s_add_u32 s6, s60, 0x2000
	s_addc_u32 s7, s61, 0
	s_mov_b32 m0, s86
	v_lshl_add_u64 v[190:191], s[6:7], 0, v[156:157]
	ds_read_b128 v[144:147], v230 offset:32768
	ds_read_b128 v[148:151], v230 offset:33792
	ds_read_b128 v[152:155], v230 offset:34816
	ds_read_b128 v[170:173], v230 offset:35840
	ds_read_b128 v[174:177], v230 offset:36864
	ds_read_b128 v[178:181], v230 offset:37888
	ds_read_b128 v[182:185], v230 offset:38912
	ds_read_b128 v[186:189], v230 offset:39936
	global_load_lds_dwordx4 v[190:191], off
	v_lshl_add_u64 v[190:191], s[6:7], 0, v[160:161]
	s_mov_b32 m0, s87
	s_nop 0
	global_load_lds_dwordx4 v[190:191], off
	s_waitcnt lgkmcnt(8)
	s_setprio 1
	s_barrier
	s_waitcnt lgkmcnt(0)
	v_mfma_f32_16x16x32_bf16 v[136:139], v[92:95], v[144:147], v[136:139]
	v_mfma_f32_16x16x32_bf16 v[124:127], v[132:135], v[144:147], v[124:127]
	v_mfma_f32_16x16x32_bf16 v[116:119], v[92:95], v[152:155], v[116:119]
	v_mfma_f32_16x16x32_bf16 v[104:107], v[132:135], v[152:155], v[104:107]
	v_mfma_f32_16x16x32_bf16 v[96:99], v[92:95], v[174:177], v[96:99]
	v_mfma_f32_16x16x32_bf16 v[84:87], v[132:135], v[174:177], v[84:87]
	v_mfma_f32_16x16x32_bf16 v[76:79], v[92:95], v[182:185], v[76:79]
	v_mfma_f32_16x16x32_bf16 v[68:71], v[132:135], v[182:185], v[68:71]
	v_mfma_f32_16x16x32_bf16 v[136:139], v[112:115], v[148:151], v[136:139]
	v_mfma_f32_16x16x32_bf16 v[124:127], v[140:143], v[148:151], v[124:127]
	v_mfma_f32_16x16x32_bf16 v[116:119], v[112:115], v[170:173], v[116:119]
	v_mfma_f32_16x16x32_bf16 v[104:107], v[140:143], v[170:173], v[104:107]
	v_mfma_f32_16x16x32_bf16 v[96:99], v[112:115], v[178:181], v[96:99]
	v_mfma_f32_16x16x32_bf16 v[84:87], v[140:143], v[178:181], v[84:87]
	v_mfma_f32_16x16x32_bf16 v[76:79], v[112:115], v[186:189], v[76:79]
	v_mfma_f32_16x16x32_bf16 v[68:71], v[140:143], v[186:189], v[68:71]
	s_barrier
	s_setprio 0
	s_add_i32 s21, 0, 0x1c000
	s_add_i32 s6, s20, s92
	v_add_u32_e32 v164, s21, v228
	v_lshl_add_u64 v[206:207], v[206:207], 0, s[42:43]
	s_mov_b32 m0, s6
	ds_read_b128 v[190:193], v164
	ds_read_b128 v[194:197], v164 offset:1024
	ds_read_b128 v[198:201], v164 offset:2048
	ds_read_b128 v[202:205], v164 offset:3072
	global_load_lds_dwordx4 v[206:207], off
	v_lshl_add_u64 v[206:207], v[208:209], 0, s[42:43]
	s_add_i32 m0, s6, 0x2000
	s_nop 0
	global_load_lds_dwordx4 v[206:207], off
	s_waitcnt lgkmcnt(0)
	s_setprio 1
	s_barrier
	v_mfma_f32_16x16x32_bf16 v[128:131], v[190:193], v[144:147], v[128:131]
	v_mfma_f32_16x16x32_bf16 v[120:123], v[198:201], v[144:147], v[120:123]
	v_mfma_f32_16x16x32_bf16 v[108:111], v[190:193], v[152:155], v[108:111]
	v_mfma_f32_16x16x32_bf16 v[100:103], v[198:201], v[152:155], v[100:103]
	v_mfma_f32_16x16x32_bf16 v[88:91], v[190:193], v[174:177], v[88:91]
	v_mfma_f32_16x16x32_bf16 v[80:83], v[198:201], v[174:177], v[80:83]
	v_mfma_f32_16x16x32_bf16 v[72:75], v[190:193], v[182:185], v[72:75]
	v_mfma_f32_16x16x32_bf16 v[64:67], v[198:201], v[182:185], v[64:67]
	v_mfma_f32_16x16x32_bf16 v[128:131], v[194:197], v[148:151], v[128:131]
	v_mfma_f32_16x16x32_bf16 v[120:123], v[202:205], v[148:151], v[120:123]
	v_mfma_f32_16x16x32_bf16 v[108:111], v[194:197], v[170:173], v[108:111]
	v_mfma_f32_16x16x32_bf16 v[100:103], v[202:205], v[170:173], v[100:103]
	v_mfma_f32_16x16x32_bf16 v[88:91], v[194:197], v[178:181], v[88:91]
	v_mfma_f32_16x16x32_bf16 v[80:83], v[202:205], v[178:181], v[80:83]
	v_mfma_f32_16x16x32_bf16 v[72:75], v[194:197], v[186:189], v[72:75]
	v_mfma_f32_16x16x32_bf16 v[64:67], v[202:205], v[186:189], v[64:67]
	s_mov_b32 m0, s97
	v_lshl_add_u64 v[206:207], v[210:211], 0, s[42:43]
	s_barrier
	s_setprio 0
	ds_read_b128 v[144:147], v230 offset:49152
	ds_read_b128 v[148:151], v230 offset:50176
	ds_read_b128 v[152:155], v230 offset:51200
	ds_read_b128 v[170:173], v230 offset:52224
	ds_read_b128 v[174:177], v230 offset:53248
	ds_read_b128 v[178:181], v230 offset:54272
	ds_read_b128 v[182:185], v230 offset:55296
	ds_read_b128 v[186:189], v230 offset:56320
	global_load_lds_dwordx4 v[206:207], off
	v_lshl_add_u64 v[206:207], v[212:213], 0, s[42:43]
	s_mov_b32 m0, s18
	s_nop 0
	global_load_lds_dwordx4 v[206:207], off
	s_waitcnt lgkmcnt(0)
	s_setprio 1
	s_barrier
	v_mfma_f32_16x16x32_bf16 v[60:63], v[92:95], v[144:147], v[60:63]
	v_mfma_f32_16x16x32_bf16 v[52:55], v[132:135], v[144:147], v[52:55]
	v_mfma_f32_16x16x32_bf16 v[44:47], v[92:95], v[152:155], v[44:47]
	v_mfma_f32_16x16x32_bf16 v[36:39], v[132:135], v[152:155], v[36:39]
	v_mfma_f32_16x16x32_bf16 v[28:31], v[92:95], v[174:177], v[28:31]
	v_mfma_f32_16x16x32_bf16 v[20:23], v[132:135], v[174:177], v[20:23]
	v_mfma_f32_16x16x32_bf16 v[12:15], v[92:95], v[182:185], v[12:15]
	v_mfma_f32_16x16x32_bf16 v[4:7], v[132:135], v[182:185], v[4:7]
	v_mfma_f32_16x16x32_bf16 v[60:63], v[112:115], v[148:151], v[60:63]
	v_mfma_f32_16x16x32_bf16 v[52:55], v[140:143], v[148:151], v[52:55]
	v_mfma_f32_16x16x32_bf16 v[44:47], v[112:115], v[170:173], v[44:47]
	v_mfma_f32_16x16x32_bf16 v[36:39], v[140:143], v[170:173], v[36:39]
	v_mfma_f32_16x16x32_bf16 v[28:31], v[112:115], v[178:181], v[28:31]
	v_mfma_f32_16x16x32_bf16 v[20:23], v[140:143], v[178:181], v[20:23]
	v_mfma_f32_16x16x32_bf16 v[12:15], v[112:115], v[186:189], v[12:15]
	v_mfma_f32_16x16x32_bf16 v[4:7], v[140:143], v[186:189], v[4:7]
	s_barrier
	s_setprio 0
	s_add_u32 s6, s8, 0x10080
	s_addc_u32 s7, s9, 0
	s_add_i32 s8, s21, s92
	v_lshl_add_u64 v[92:93], s[6:7], 0, v[158:159]
	s_mov_b32 m0, s8
	s_nop 0
	global_load_lds_dwordx4 v[92:93], off
	v_lshl_add_u64 v[92:93], s[6:7], 0, v[162:163]
	s_add_i32 m0, s8, 0x2000
	s_nop 0
	global_load_lds_dwordx4 v[92:93], off
	s_waitcnt vmcnt(6)
	s_setprio 1
	s_barrier
	v_mfma_f32_16x16x32_bf16 v[56:59], v[190:193], v[144:147], v[56:59]
	v_mfma_f32_16x16x32_bf16 v[48:51], v[198:201], v[144:147], v[48:51]
	v_mfma_f32_16x16x32_bf16 v[40:43], v[190:193], v[152:155], v[40:43]
	v_mfma_f32_16x16x32_bf16 v[32:35], v[198:201], v[152:155], v[32:35]
	v_mfma_f32_16x16x32_bf16 v[24:27], v[190:193], v[174:177], v[24:27]
	v_mfma_f32_16x16x32_bf16 v[16:19], v[198:201], v[174:177], v[16:19]
	v_mfma_f32_16x16x32_bf16 v[8:11], v[190:193], v[182:185], v[8:11]
	v_mfma_f32_16x16x32_bf16 v[0:3], v[198:201], v[182:185], v[0:3]
	v_mfma_f32_16x16x32_bf16 v[56:59], v[194:197], v[148:151], v[56:59]
	v_mfma_f32_16x16x32_bf16 v[48:51], v[202:205], v[148:151], v[48:51]
	v_mfma_f32_16x16x32_bf16 v[40:43], v[194:197], v[170:173], v[40:43]
	v_mfma_f32_16x16x32_bf16 v[32:35], v[202:205], v[170:173], v[32:35]
	v_mfma_f32_16x16x32_bf16 v[24:27], v[194:197], v[178:181], v[24:27]
	v_mfma_f32_16x16x32_bf16 v[16:19], v[202:205], v[178:181], v[16:19]
	v_mfma_f32_16x16x32_bf16 v[8:11], v[194:197], v[186:189], v[8:11]
	v_mfma_f32_16x16x32_bf16 v[0:3], v[202:205], v[186:189], v[0:3]
	s_add_u32 s64, s64, 0x100
	s_addc_u32 s65, s65, 0
	s_cmp_lt_i32 s66, s95
	s_mov_b64 s[6:7], s[4:5]
	s_mov_b32 s8, s66
	s_barrier
	s_setprio 0
	s_cbranch_scc0 .Lpeel_done_P4

.Lpeel_done_P4:
	v_lshl_add_u64 v[190:191], s[56:57], 0, v[166:167]
	s_add_i32 m0, s93, 0xc000
	s_nop 0
	global_load_lds_dwordx4 v[190:191], off
	v_lshl_add_u64 v[192:193], s[56:57], 0, v[168:169]
	s_add_i32 m0, s93, 0xe000
	s_nop 0
	global_load_lds_dwordx4 v[192:193], off
